# GLA items: item->workgroup map permuted so the 8 (head,half) items of a batch run on one XCD (shared q/k/g_low rows hit L2)
# speedup vs baseline: 1.0149x; 1.0037x over previous
; #define LAS __attribute__((address_space(3)))
; DI bf16_t f2bf(float f) { return (bf16_t)(cvt_pk_bf16(f, 0.f) & 0xffffu); }
; DI void gla_item(ldsp lds, const Params& p, const bf16_t* proj, bf16_t* obuf, const float* q0k0, int jl, int item, int tid, int wid, int lane) {
;     const int half = item & 1, h = (item >> 1) & 3, b = item >> 3;
;     constexpr int O_GL = 0, O_WG = 5120, O_BG = 12800, O_LA = 13312, O_QI = 38912, O_KI = 52224, O_KO = 65536, O_V = 78848, O_AM = 92160, O_ST = 101376;
;     constexpr int S96 = 208, SGL = 80, SAM = 144, SLA = 100;
;     const ldsp GL = lds + O_GL, WG = lds + O_WG, QI = lds + O_QI, KI = lds + O_KI, KO = lds + O_KO, Vl = lds + O_V, AM = lds + O_AM, ST = lds + O_ST;
;     LAS float* BG = (LAS float*)(lds + O_BG);
;     LAS float* LA = (LAS float*)(lds + O_LA);
;     const int li = lane & 15, quad = lane >> 4;
;     {
;         float wv6[6];
; #pragma unroll
;         for (int i = 0; i < 6; ++i) { const int e = tid + i * 512, d = e >> 5, kk = e & 31;
;             wv6[i] = kk < 16 ? p.w_gate_up[(size_t)(jl * 16 + kk) * 384 + h * 96 + d] : 0.f; }
; #pragma unroll
;         for (int i = 0; i < 6; ++i) { const int e = tid + i * 512, d = e >> 5, kk = e & 31; *(LAS bf16_t*)(WG + d * SGL + kk * 2) = f2bf(wv6[i]); }
;     }
;     for (int e = tid; e < 64 * 40; e += 512) *(LAS bf16_t*)(GL + e * 2) = 0;
;     if (tid < 96) BG[tid] = p.b_gate[jl * 384 + h * 96 + tid];
;     float a00;
;     {
;         const float* qp = q0k0 + b * 768 + h * 96; const float* kp = qp + 384;
;         float t = qp[lane] * kp[lane] + (lane < 32 ? qp[64 + lane] * kp[64 + lane] : 0.f);
;         a00 = wave_sum(t) * 0.10206207261596575f;
;     }
;     f32x4 S[6];
; #pragma unroll
;     for (int i = 0; i < 6; ++i) S[i] = (f32x4){0.f, 0.f, 0.f, 0.f};
;     __syncthreads();
;     const int c0 = tid, c1 = tid + 512;
;     const int row0 = c0 / 12, ch0 = c0 - row0 * 12, row1 = c1 / 12, ch1 = c1 - row1 * 12;
;     const bool has1 = tid < 256;
;     u32x4 qreg0, kreg0, vreg0, qreg1 = (u32x4){0u, 0u, 0u, 0u}, kreg1 = qreg1, vreg1 = qreg1, greg = qreg1;
.LBB0_448:
	s_and_b64 vcc, exec, s[22:23]
	s_cbranch_vccz .LBB0_652
	v_readlane_b32 s14, v251, 52
	v_readlane_b32 s15, v251, 53
	v_lshrrev_b32_e32 v145, 4, v238
	v_and_b32_e32 v69, 48, v32
	s_waitcnt vmcnt(0)
	v_or_b32_e32 v1, 48, v238
	s_mov_b32 s70, s93
	s_andn2_b64 vcc, exec, s[14:15]
	v_bfe_u32 v144, v32, 2, 2
	v_lshlrev_b32_e32 v68, 3, v145
	v_add_u32_e32 v89, 0, v69
	v_mul_u32_u24_e32 v93, 0x90, v1
	v_readlane_b32 s76, v255, 15
	s_cbranch_vccnz .LBB0_504
	v_readlane_b32 s40, v254, 15
	v_readlane_b32 s14, v254, 63
	v_and_b32_e32 v0, 31, v32
	v_readlane_b32 s54, v254, 29
	v_readlane_b32 s55, v254, 30
	v_readlane_b32 s15, v255, 0
	v_cmp_gt_u32_e64 s[38:39], 16, v0
	v_lshl_add_u32 v0, s14, 4, v0
	v_mov_b64_e32 v[2:3], s[54:55]
	s_movk_i32 s22, 0x600
	s_mul_i32 s0, s14, 0x180
	v_mad_u64_u32 v[70:71], s[14:15], v0, s22, v[2:3]
	v_add_u32_e32 v2, 0x800, v32
	v_ashrrev_i32_e32 v80, 5, v2
	v_add_u32_e32 v2, 0xa00, v32
	v_lshlrev_b32_e32 v147, 1, v32
	v_ashrrev_i32_e32 v82, 5, v2
	v_and_b32_e32 v2, 62, v147
	v_and_b32_e32 v11, 64, v233
	v_add_u32_e32 v13, 0, v2
	v_add_u32_e32 v2, 64, v11
	v_xor_b32_e32 v3, 32, v233
	v_cmp_lt_i32_e32 vcc, v3, v2
	v_add_u32_e32 v0, 0x200, v32
	v_add_u32_e32 v34, 0x400, v32
	v_cndmask_b32_e32 v3, v233, v3, vcc
	v_lshlrev_b32_e32 v150, 2, v3
	v_xor_b32_e32 v3, 16, v233
	v_cmp_lt_i32_e32 vcc, v3, v2
	v_add_u32_e32 v35, 0x600, v32
	v_add_u32_e32 v148, s0, v32
	v_cndmask_b32_e32 v3, v233, v3, vcc
	v_lshlrev_b32_e32 v151, 2, v3
	v_xor_b32_e32 v3, 8, v233
	v_cmp_lt_i32_e32 vcc, v3, v2
	s_mov_b32 s0, 0x2aaaaaab
	v_ashrrev_i32_e32 v72, 5, v32
	v_cndmask_b32_e32 v3, v233, v3, vcc
	v_lshlrev_b32_e32 v152, 2, v3
	v_xor_b32_e32 v3, 4, v233
	v_cmp_lt_i32_e32 vcc, v3, v2
	v_ashrrev_i32_e32 v74, 5, v0
	v_ashrrev_i32_e32 v76, 5, v34
	v_cndmask_b32_e32 v3, v233, v3, vcc
	v_lshlrev_b32_e32 v153, 2, v3
	v_xor_b32_e32 v3, 2, v233
	v_cmp_lt_i32_e32 vcc, v3, v2
	v_ashrrev_i32_e32 v78, 5, v35
	s_movk_i32 s14, 0x50
	v_cndmask_b32_e32 v3, v233, v3, vcc
	v_lshlrev_b32_e32 v155, 2, v3
	v_xor_b32_e32 v3, 1, v233
	v_cmp_lt_i32_e32 vcc, v3, v2
	v_readlane_b32 s41, v254, 16
	v_mul_lo_u32 v18, v72, s14
	v_cndmask_b32_e32 v2, v233, v3, vcc
	v_lshlrev_b32_e32 v156, 2, v2
	v_mul_hi_i32 v2, v32, s0
	v_mul_lo_u32 v19, v74, s14
	v_mul_lo_u32 v20, v76, s14
	v_mul_lo_u32 v21, v78, s14
	v_mul_lo_u32 v22, v80, s14
	v_mul_lo_u32 v23, v82, s14
	s_movk_i32 s14, 0xa00
	v_lshrrev_b32_e32 v3, 31, v2
	v_ashrrev_i32_e32 v2, 1, v2
	v_readlane_b32 s42, v254, 17
	v_readlane_b32 s43, v254, 18
	v_cmp_gt_i32_e64 s[40:41], s14, v32
	s_movk_i32 s14, 0x60
	v_add_u32_e32 v84, v2, v3
	v_cmp_gt_i32_e64 s[42:43], s14, v32
	v_mad_u64_u32 v[2:3], s[14:15], v84, -12, v[32:33]
	v_mul_hi_i32 v3, v0, s0
	v_readlane_b32 s46, v254, 21
	v_readlane_b32 s47, v254, 22
	v_lshrrev_b32_e32 v4, 31, v3
	v_ashrrev_i32_e32 v3, 1, v3
	s_movk_i32 s0, 0x100
	v_readlane_b32 s48, v254, 23
	v_readlane_b32 s49, v254, 24
	v_add_u32_e32 v86, v3, v4
	v_cmp_gt_i32_e64 s[46:47], s0, v32
	s_movk_i32 s0, 0x80
	s_cmp_lt_i32 s16, 6
	v_readlane_b32 s31, v255, 14
	v_mad_u64_u32 v[4:5], s[14:15], v86, -12, v[0:1]
	v_cmp_gt_i32_e64 s[48:49], s0, v32
	s_cselect_b64 s[36:37], -1, 0
	s_bfe_u32 s0, s31, 0x20006
	s_lshl_b32 s14, s0, 5
	v_readlane_b32 s19, v254, 48
	s_add_i32 s14, s19, s14
	v_and_b32_e32 v146, 15, v32
	v_add_u32_e32 v26, s14, v68
	s_lshl_b32 s14, s0, 4
	s_movk_i32 s23, 0xd0
	v_or_b32_e32 v3, s14, v146
	v_mad_u32_u24 v27, v3, s23, 0
	v_lshlrev_b32_e32 v3, 4, v32
	s_lshl_b32 s26, s16, 4
	v_and_b32_e32 v10, 16, v3
	v_or_b32_e32 v3, s26, v146
	v_add_u32_e32 v14, -16, v233
	v_lshl_or_b32 v17, v145, 2, s14
	v_lshl_add_u32 v92, v3, 2, 0
	s_movk_i32 s14, 0x4c
	v_cmp_lt_i32_e32 vcc, v14, v11
	v_mad_u64_u32 v[94:95], s[14:15], v3, s14, v[92:93]
	s_nop 0
	v_cndmask_b32_e32 v14, v14, v233, vcc
	v_lshlrev_b32_e32 v95, 2, v14
	v_subrev_u32_e32 v14, 32, v233
	v_cmp_lt_i32_e32 vcc, v14, v11
	s_movk_i32 s14, 0xffb4
	v_mul_lo_u32 v5, v84, s23
	v_cndmask_b32_e32 v14, v14, v233, vcc
	v_lshlrev_b32_e32 v163, 2, v14
	v_mad_u64_u32 v[14:15], s[14:15], v3, s14, v[94:95]
	v_mul_lo_u32 v3, v3, s23
	v_readlane_b32 s14, v254, 49
	v_readlane_b32 s17, v254, 47
	v_mul_lo_u32 v30, v86, s23
	v_add_u32_e32 v165, s14, v3
	v_lshlrev_b32_e32 v3, 2, v238
	v_and_b32_e32 v15, 12, v3
	v_or_b32_e32 v3, s26, v15
	v_add_u32_e32 v24, s17, v5
	v_add_u32_e32 v31, s17, v30
	v_lshl_add_u32 v37, v3, 1, s17
	s_movk_i32 s17, 0x190
	v_mul_lo_u32 v3, v84, s17
	v_lshlrev_b32_e32 v6, 3, v2
	v_lshlrev_b32_e32 v25, 4, v2
	v_add_u32_e32 v16, 0, v3
	v_lshlrev_b32_e32 v2, 5, v2
	s_movk_i32 s30, 0xff40
	v_add_u32_e32 v38, s19, v69
	v_add_u32_e32 v166, v16, v2
	v_add_u32_e32 v167, 0, v2
	v_mad_u64_u32 v[2:3], s[14:15], v84, s30, v[16:17]
	s_add_i32 s19, 0, 0x10000
	v_add_u32_e32 v3, s19, v5
	v_mul_lo_u32 v5, v86, s17
	v_lshlrev_b32_e32 v8, 3, v4
	v_lshlrev_b32_e32 v36, 4, v4
	v_add_u32_e32 v16, 0, v5
	v_lshlrev_b32_e32 v4, 5, v4
	v_add_u32_e32 v168, v16, v4
	v_add_u32_e32 v169, 0, v4
	v_mad_u64_u32 v[4:5], s[14:15], v86, s30, v[16:17]
	s_ashr_i32 s27, s26, 31
	s_ashr_i32 s14, s31, 8
	s_cmp_le_i32 s0, s14
	s_cselect_b64 s[30:31], -1, 0
	s_add_i32 s17, s16, 8
	v_or_b32_e32 v11, v11, v1
	v_mul_u32_u24_e32 v41, 0x50, v1
	v_add_u32_e32 v5, s19, v30
	v_lshl_or_b32 v30, s14, 4, v146
	s_ashr_i32 s14, s17, 2
	s_waitcnt lgkmcnt(0)
; DI void gla_item(ldsp lds, const Params& p, const bf16_t* proj, bf16_t* obuf, const float* q0k0, int jl, int item, int tid, int wid, int lane) {
;     ...
;     const int c0 = tid, c1 = tid + 512;
;     const int row0 = c0 / 12, ch0 = c0 - row0 * 12, row1 = c1 / 12, ch1 = c1 - row1 * 12;
;     const bool has1 = tid < 256;
;     u32x4 qreg0, kreg0, vreg0, qreg1 = (u32x4){0u, 0u, 0u, 0u}, kreg1 = qreg1, vreg1 = qreg1, greg = qreg1;
;     ...
;     GLA_LOAD_CHUNK(0);
;     for (int n = 0; n < 32; ++n) {
; __global__ void __launch_bounds__(NTHREADS, 2) megak(Params p) {
;     ...
;                 for (int it = blockIdx.x; it < BATCH * 8; it += gridDim.x) gla_item(lds, p, PROJ, OBUF, Q0K0, jl, it, tid, wid, lane);
	v_mul_u32_u24_e32 v45, 0xd0, v1
	v_max_i32_e32 v1, 0x800, v32
	v_mul_lo_u32 v16, v30, s23
	s_cmp_le_i32 s0, s14
	v_lshl_or_b32 v33, s14, 4, v146
	v_sub_u32_e32 v1, v1, v32
	v_add_u32_e32 v42, 0, v16
	s_cselect_b64 s[72:73], -1, 0
	v_mul_lo_u32 v16, v33, s23
	s_lshl_b64 s[14:15], s[26:27], 1
	v_add_u32_e32 v47, 0x1ff, v1
	v_ashrrev_i32_e32 v9, 31, v8
	v_or_b32_e32 v28, 2, v17
	v_or_b32_e32 v29, 3, v17
	v_lshlrev_b32_e32 v164, 2, v11
	v_or_b32_e32 v11, v68, v144
	v_cmp_gt_i32_e64 s[54:55], v17, v30
	v_cmp_lt_i32_e64 s[56:57], v17, v30
	v_add_u32_e32 v43, 0, v16
	v_cmp_gt_i32_e64 s[62:63], v17, v33
	v_cmp_lt_i32_e64 s[64:65], v17, v33
	v_mov_b64_e32 v[16:17], s[14:15]
	s_movk_i32 s0, 0x90
	v_lshrrev_b32_e32 v1, 9, v47
	v_readlane_b32 s14, v251, 15
	v_cmp_gt_i32_e64 s[58:59], v28, v30
	v_cmp_gt_i32_e64 s[66:67], v28, v33
	v_cmp_gt_i32_e64 s[68:69], v29, v33
	v_mul_u32_u24_e32 v28, 0xd0, v11
	v_mul_lo_u32 v46, v33, s0
	v_add_u32_e32 v48, 1, v1
	v_mov_b32_e32 v33, v0
	v_mov_b32_e32 v11, v12
	v_readlane_b32 s15, v251, 16
	v_lshlrev_b64 v[98:99], 1, v[8:9]
	v_mov_b64_e32 v[0:1], 0x68a0600
	s_waitcnt lgkmcnt(0)
	v_ashrrev_i32_e32 v7, 31, v6
	v_lshl_add_u64 v[96:97], s[14:15], 0, v[10:11]
	v_mad_i64_i32 v[100:101], s[14:15], v86, s94, v[0:1]
	v_mad_i64_i32 v[104:105], s[14:15], v86, s94, v[98:99]
	v_and_b32_e32 v0, 1, v32
	v_mov_b32_e32 v1, 0x68a0c00
	v_lshl_or_b32 v106, v0, 4, v1
	v_lshlrev_b64 v[108:109], 1, v[6:7]
	s_mov_b64 s[14:15], 0x68a0600
	v_mov_b64_e32 v[0:1], s[6:7]
	v_lshl_add_u64 v[110:111], v[108:109], 0, s[14:15]
	v_mad_i64_i32 v[112:113], s[14:15], v84, s94, v[0:1]
	v_mul_u32_u24_e32 v6, 0x600, v146
	v_lshrrev_b32_e32 v0, 1, v69
	v_mad_i64_i32 v[114:115], s[14:15], v84, s94, v[108:109]
	v_or_b32_e32 v116, v6, v0
	v_mad_u64_u32 v[6:7], s[14:15], v146, s22, v[16:17]
	v_cmp_gt_i32_e64 s[60:61], v29, v30
	v_mul_lo_u32 v30, v30, s0
	s_mov_b64 s[14:15], 0x26840000
	s_movk_i32 s0, 0x5ff
	v_lshl_add_u64 v[118:119], v[6:7], 0, s[14:15]
	v_cmp_lt_u32_e64 s[14:15], s0, v47
	v_and_b32_e32 v170, 0xfffffc, v48
	v_readlane_b32 s44, v254, 19
	v_writelane_b32 v255, s14, 17
	v_readlane_b32 s45, v254, 20
	v_readlane_b32 s50, v254, 25
	v_writelane_b32 v255, s15, 18
	v_cmp_ne_u32_e64 s[14:15], v48, v170
	v_readlane_b32 s51, v254, 26
	v_readlane_b32 s52, v254, 27
	v_readlane_b32 s53, v254, 28
	v_ashrrev_i32_e32 v90, 1, v32
	v_mul_u32_u24_e32 v39, 0x50, v146
	v_mul_u32_u24_e32 v40, 0x640, v145
	v_lshl_add_u32 v15, v15, 1, s19
	v_mul_u32_u24_e32 v29, 0x90, v146
	v_mul_u32_u24_e32 v44, 0xd0, v146
	v_mov_b32_e32 v1, v12
	v_writelane_b32 v255, s14, 19
	v_ashrrev_i32_e32 v73, 31, v72
	v_ashrrev_i32_e32 v75, 31, v74
	v_ashrrev_i32_e32 v77, 31, v76
	v_ashrrev_i32_e32 v79, 31, v78
	v_ashrrev_i32_e32 v81, 31, v80
	v_ashrrev_i32_e32 v83, 31, v82
	s_movk_i32 s71, 0x50
	v_lshl_add_u32 v149, v32, 2, 0
	v_cmp_gt_u32_e64 s[44:45], 32, v238
	v_ashrrev_i32_e32 v85, 31, v84
	v_ashrrev_i32_e32 v87, 31, v86
	v_lshrrev_b32_e32 v88, 1, v32
	v_ashrrev_i32_e32 v91, 31, v90
	v_cmp_gt_u32_e64 s[50:51], 16, v238
	v_add_u32_e32 v162, 0, v10
	v_cmp_lt_u32_e64 s[52:53], 31, v238
	v_lshl_add_u32 v171, v170, 9, v32
	v_lshl_add_u64 v[102:103], s[6:7], 0, v[98:99]
	v_mov_b32_e32 v107, v12
	v_mul_hi_u32_u24_e32 v117, 0x600, v146
	v_lshl_add_u64 v[120:121], s[6:7], 0, v[0:1]
	v_add_u32_e32 v172, v13, v18
	v_add_u32_e32 v173, v13, v19
	v_add_u32_e32 v174, v13, v20
	v_add_u32_e32 v175, v13, v21
	v_add_u32_e32 v176, v13, v22
	v_add_u32_e32 v177, v13, v23
	v_lshlrev_b32_e32 v122, 2, v238
	v_add_u32_e32 v178, v24, v25
	v_add_u32_e32 v179, v31, v36
	v_add_u32_e32 v180, v89, v39
	v_add_u32_e32 v181, v14, v40
	v_add_u32_e32 v182, v89, v41
	v_add_u32_e32 v183, v2, v25
	v_add_u32_e32 v184, v3, v25
	v_add_u32_e32 v185, v4, v36
	v_add_u32_e32 v186, v5, v36
	v_add_u32_e32 v187, v42, v69
	v_add_u32_e32 v188, v26, v30
	v_add_u32_e32 v189, v43, v69
	v_add_u32_e32 v190, v26, v46
	v_add_u32_e32 v191, v37, v28
	v_add_u32_e32 v192, v38, v29
	v_add_u32_e32 v193, v38, v93
	v_add_u32_e32 v194, v89, v44
	v_add_u32_e32 v195, v89, v45
	v_add_u32_e32 v196, v15, v28
	v_add_u32_e32 v197, v27, v69
	v_readlane_b32 s19, v254, 54
	v_writelane_b32 v255, s15, 20
	s_and_b32 s98, s19, 7
	s_lshl_b32 s98, s98, 5
	s_lshr_b32 s19, s19, 3
	s_or_b32 s19, s19, s98
	s_branch .LBB0_452
